# v65 + plain GEMM store epilogues: the per-row-group rotary default cos/sin (1,0,1,0) v_mov groups deleted (46 groups; only ever consumed under the rotary flag, which reloads them)
# baseline (speedup 1.0000x reference)
.LBB0_295:
	v_lshl_add_u32 v152, s40, 8, v1
	s_cmp_lt_i32 s38, 0
	s_cselect_b64 s[40:41], -1, 0
	s_cmp_gt_i32 s38, -1
	v_ashrrev_i32_e32 v153, 31, v152
	s_cbranch_scc0 .LBB0_338
	v_cndmask_b32_e64 v154, 0, 1, s[40:41]
	v_cmp_ne_u32_e64 s[36:37], 1, v154
	s_andn2_b64 vcc, exec, s[40:41]
	s_cbranch_vccnz .LBB0_298

.LBB0_300:
	v_or_b32_e32 v122, 16, v152
	s_and_b64 vcc, exec, s[36:37]
	v_ashrrev_i32_e32 v123, 31, v122
	v_cvt_pk_bf16_f32 v118, v118, v119
	v_cvt_pk_bf16_f32 v119, v120, v121
	v_cvt_pk_bf16_f32 v120, v114, v115
	v_cvt_pk_bf16_f32 v121, v116, v117
	global_store_dwordx4 v[154:155], v[118:121], off offset:256
	s_cbranch_vccz .LBB0_339
	s_nop 0
	s_and_b64 vcc, exec, s[36:37]
	s_cbranch_vccnz .LBB0_303

.LBB0_305:
	v_or_b32_e32 v106, 32, v152
	s_and_b64 vcc, exec, s[36:37]
	v_ashrrev_i32_e32 v107, 31, v106
	v_cvt_pk_bf16_f32 v102, v102, v103
	v_cvt_pk_bf16_f32 v103, v104, v105
	v_cvt_pk_bf16_f32 v104, v98, v99
	v_cvt_pk_bf16_f32 v105, v100, v101
	global_store_dwordx4 v[122:123], v[102:105], off offset:256
	s_cbranch_vccz .LBB0_340
	s_nop 0
	s_and_b64 vcc, exec, s[36:37]
	s_cbranch_vccnz .LBB0_308

.LBB0_310:
	v_or_b32_e32 v90, 48, v152
	s_and_b64 vcc, exec, s[36:37]
	v_ashrrev_i32_e32 v91, 31, v90
	v_cvt_pk_bf16_f32 v86, v86, v87
	v_cvt_pk_bf16_f32 v87, v88, v89
	v_cvt_pk_bf16_f32 v88, v82, v83
	v_cvt_pk_bf16_f32 v89, v84, v85
	global_store_dwordx4 v[106:107], v[86:89], off offset:256
	s_cbranch_vccz .LBB0_341
	s_nop 0
	s_and_b64 vcc, exec, s[36:37]
	s_cbranch_vccnz .LBB0_313

.LBB0_315:
	v_add_u32_e32 v74, 0x80, v152
	s_and_b64 vcc, exec, s[36:37]
	v_ashrrev_i32_e32 v75, 31, v74
	v_cvt_pk_bf16_f32 v70, v70, v71
	v_cvt_pk_bf16_f32 v71, v72, v73
	v_cvt_pk_bf16_f32 v72, v66, v67
	v_cvt_pk_bf16_f32 v73, v68, v69
	global_store_dwordx4 v[90:91], v[70:73], off offset:256
	s_cbranch_vccz .LBB0_342
	s_nop 0
	s_and_b64 vcc, exec, s[36:37]
	s_cbranch_vccnz .LBB0_318

.LBB0_320:
	v_add_u32_e32 v58, 0x90, v152
	s_and_b64 vcc, exec, s[36:37]
	v_ashrrev_i32_e32 v59, 31, v58
	v_cvt_pk_bf16_f32 v54, v54, v55
	v_cvt_pk_bf16_f32 v55, v56, v57
	v_cvt_pk_bf16_f32 v56, v50, v51
	v_cvt_pk_bf16_f32 v57, v52, v53
	global_store_dwordx4 v[74:75], v[54:57], off offset:256
	s_cbranch_vccz .LBB0_343
	s_nop 0
	s_and_b64 vcc, exec, s[36:37]
	s_cbranch_vccnz .LBB0_323

.LBB0_325:
	v_add_u32_e32 v42, 0xa0, v152
	s_and_b64 vcc, exec, s[36:37]
	v_ashrrev_i32_e32 v43, 31, v42
	v_cvt_pk_bf16_f32 v38, v38, v39
	v_cvt_pk_bf16_f32 v39, v40, v41
	v_cvt_pk_bf16_f32 v40, v34, v35
	v_cvt_pk_bf16_f32 v41, v36, v37
	global_store_dwordx4 v[58:59], v[38:41], off offset:256
	s_cbranch_vccz .LBB0_344
	s_nop 0
	s_and_b64 vcc, exec, s[36:37]
	s_cbranch_vccnz .LBB0_328

.LBB0_330:
	v_add_u32_e32 v26, 0xb0, v152
	s_and_b64 vcc, exec, s[36:37]
	v_ashrrev_i32_e32 v27, 31, v26
	v_cvt_pk_bf16_f32 v22, v22, v23
	v_cvt_pk_bf16_f32 v23, v24, v25
	v_cvt_pk_bf16_f32 v24, v18, v19
	v_cvt_pk_bf16_f32 v25, v20, v21
	global_store_dwordx4 v[42:43], v[22:25], off offset:256
	s_cbranch_vccz .LBB0_345
	s_nop 0
	s_and_b64 vcc, exec, s[36:37]
	s_cbranch_vccnz .LBB0_333

.LBB0_370:
.LBB0_371:
	v_pk_mul_f32 v[126:127], v[160:161], v[112:113] op_sel:[1,0]
	v_pk_mul_f32 v[110:111], v[160:161], v[110:111] op_sel:[1,0]
	v_pk_mul_f32 v[112:113], v[160:161], v[108:109] op_sel:[1,0]
	s_and_b64 vcc, exec, s[36:37]
	v_pk_mul_f32 v[108:109], v[160:161], v[106:107] op_sel:[1,0]
	s_cbranch_vccnz .LBB0_373
	s_waitcnt vmcnt(0)
	v_pk_mul_f32 v[128:129], v[110:111], v[118:119] op_sel:[1,1] op_sel_hi:[0,1]
	v_pk_mul_f32 v[106:107], v[110:111], v[118:119]
	v_pk_fma_f32 v[110:111], v[110:111], v[118:119], v[128:129] op_sel_hi:[1,0,1]
	v_pk_mul_f32 v[134:135], v[108:109], v[114:115] op_sel:[1,1] op_sel_hi:[0,1]
	v_mul_f32_e32 v110, v127, v121
	v_pk_fma_f32 v[130:131], v[126:127], v[120:121], v[110:111] op_sel_hi:[1,1,0] neg_lo:[0,0,1] neg_hi:[0,0,1]
	v_mul_f32_e32 v110, v126, v121
	v_pk_fma_f32 v[132:133], v[126:127], v[120:121], v[110:111] op_sel:[1,0,0] op_sel_hi:[0,1,0]
	v_pk_mul_f32 v[126:127], v[108:109], v[114:115]
	v_pk_fma_f32 v[108:109], v[108:109], v[114:115], v[134:135] op_sel_hi:[1,0,1]
	v_sub_f32_e32 v110, v106, v128
	v_mul_f32_e32 v108, v113, v117
	v_pk_fma_f32 v[136:137], v[112:113], v[116:117], v[108:109] op_sel_hi:[1,1,0] neg_lo:[0,0,1] neg_hi:[0,0,1]
	v_mul_f32_e32 v108, v112, v117
	v_pk_fma_f32 v[166:167], v[112:113], v[116:117], v[108:109] op_sel:[1,0,0] op_sel_hi:[0,1,0]
	v_sub_f32_e32 v108, v126, v134
	v_mov_b32_e32 v126, v130
	v_mov_b32_e32 v127, v132
	v_mov_b32_e32 v112, v136
	v_mov_b32_e32 v113, v166

.LBB0_377:
.LBB0_378:
	v_pk_mul_f32 v[108:109], v[158:159], v[96:97] op_sel_hi:[0,1]
	v_pk_mul_f32 v[94:95], v[158:159], v[94:95] op_sel_hi:[0,1]
	v_pk_mul_f32 v[96:97], v[158:159], v[92:93] op_sel_hi:[0,1]
	s_and_b64 vcc, exec, s[36:37]
	v_pk_mul_f32 v[92:93], v[158:159], v[90:91] op_sel_hi:[0,1]
	s_cbranch_vccnz .LBB0_380
	s_waitcnt vmcnt(0)
	v_pk_mul_f32 v[110:111], v[94:95], v[102:103] op_sel:[1,1] op_sel_hi:[0,1]
	v_pk_mul_f32 v[90:91], v[94:95], v[102:103]
	v_pk_fma_f32 v[94:95], v[94:95], v[102:103], v[110:111] op_sel_hi:[1,0,1]
	v_pk_mul_f32 v[116:117], v[92:93], v[98:99] op_sel:[1,1] op_sel_hi:[0,1]
	v_mul_f32_e32 v94, v109, v105
	v_pk_fma_f32 v[112:113], v[108:109], v[104:105], v[94:95] op_sel_hi:[1,1,0] neg_lo:[0,0,1] neg_hi:[0,0,1]
	v_mul_f32_e32 v94, v108, v105
	v_pk_fma_f32 v[114:115], v[108:109], v[104:105], v[94:95] op_sel:[1,0,0] op_sel_hi:[0,1,0]
	v_pk_mul_f32 v[108:109], v[92:93], v[98:99]
	v_pk_fma_f32 v[92:93], v[92:93], v[98:99], v[116:117] op_sel_hi:[1,0,1]
	v_sub_f32_e32 v94, v90, v110
	v_mul_f32_e32 v92, v97, v101
	v_pk_fma_f32 v[118:119], v[96:97], v[100:101], v[92:93] op_sel_hi:[1,1,0] neg_lo:[0,0,1] neg_hi:[0,0,1]
	v_mul_f32_e32 v92, v96, v101
	v_pk_fma_f32 v[120:121], v[96:97], v[100:101], v[92:93] op_sel:[1,0,0] op_sel_hi:[0,1,0]
	v_sub_f32_e32 v92, v108, v116
	v_mov_b32_e32 v108, v112
	v_mov_b32_e32 v109, v114
	v_mov_b32_e32 v96, v118
	v_mov_b32_e32 v97, v120

.LBB0_384:
.LBB0_385:
	v_pk_mul_f32 v[92:93], v[156:157], v[80:81] op_sel_hi:[0,1]
	v_pk_mul_f32 v[78:79], v[156:157], v[78:79] op_sel_hi:[0,1]
	v_pk_mul_f32 v[80:81], v[156:157], v[76:77] op_sel_hi:[0,1]
	s_and_b64 vcc, exec, s[36:37]
	v_pk_mul_f32 v[76:77], v[156:157], v[74:75] op_sel_hi:[0,1]
	s_cbranch_vccnz .LBB0_387
	s_waitcnt vmcnt(0)
	v_pk_mul_f32 v[94:95], v[78:79], v[86:87] op_sel:[1,1] op_sel_hi:[0,1]
	v_pk_mul_f32 v[74:75], v[78:79], v[86:87]
	v_pk_fma_f32 v[78:79], v[78:79], v[86:87], v[94:95] op_sel_hi:[1,0,1]
	v_pk_mul_f32 v[100:101], v[76:77], v[82:83] op_sel:[1,1] op_sel_hi:[0,1]
	v_mul_f32_e32 v78, v93, v89
	v_pk_fma_f32 v[96:97], v[92:93], v[88:89], v[78:79] op_sel_hi:[1,1,0] neg_lo:[0,0,1] neg_hi:[0,0,1]
	v_mul_f32_e32 v78, v92, v89
	v_pk_fma_f32 v[98:99], v[92:93], v[88:89], v[78:79] op_sel:[1,0,0] op_sel_hi:[0,1,0]
	v_pk_mul_f32 v[92:93], v[76:77], v[82:83]
	v_pk_fma_f32 v[76:77], v[76:77], v[82:83], v[100:101] op_sel_hi:[1,0,1]
	v_sub_f32_e32 v78, v74, v94
	v_mul_f32_e32 v76, v81, v85
	v_pk_fma_f32 v[102:103], v[80:81], v[84:85], v[76:77] op_sel_hi:[1,1,0] neg_lo:[0,0,1] neg_hi:[0,0,1]
	v_mul_f32_e32 v76, v80, v85
	v_pk_fma_f32 v[104:105], v[80:81], v[84:85], v[76:77] op_sel:[1,0,0] op_sel_hi:[0,1,0]
	v_sub_f32_e32 v76, v92, v100
	v_mov_b32_e32 v92, v96
	v_mov_b32_e32 v93, v98
	v_mov_b32_e32 v80, v102
	v_mov_b32_e32 v81, v104

.LBB0_391:
.LBB0_392:
	v_pk_mul_f32 v[76:77], v[154:155], v[64:65] op_sel_hi:[0,1]
	v_pk_mul_f32 v[62:63], v[154:155], v[62:63] op_sel_hi:[0,1]
	v_pk_mul_f32 v[64:65], v[154:155], v[60:61] op_sel_hi:[0,1]
	s_and_b64 vcc, exec, s[36:37]
	v_pk_mul_f32 v[60:61], v[154:155], v[58:59] op_sel_hi:[0,1]
	s_cbranch_vccnz .LBB0_394
	s_waitcnt vmcnt(0)
	v_pk_mul_f32 v[78:79], v[62:63], v[70:71] op_sel:[1,1] op_sel_hi:[0,1]
	v_pk_mul_f32 v[58:59], v[62:63], v[70:71]
	v_pk_fma_f32 v[62:63], v[62:63], v[70:71], v[78:79] op_sel_hi:[1,0,1]
	v_pk_mul_f32 v[84:85], v[60:61], v[66:67] op_sel:[1,1] op_sel_hi:[0,1]
	v_mul_f32_e32 v62, v77, v73
	v_pk_fma_f32 v[80:81], v[76:77], v[72:73], v[62:63] op_sel_hi:[1,1,0] neg_lo:[0,0,1] neg_hi:[0,0,1]
	v_mul_f32_e32 v62, v76, v73
	v_pk_fma_f32 v[82:83], v[76:77], v[72:73], v[62:63] op_sel:[1,0,0] op_sel_hi:[0,1,0]
	v_pk_mul_f32 v[76:77], v[60:61], v[66:67]
	v_pk_fma_f32 v[60:61], v[60:61], v[66:67], v[84:85] op_sel_hi:[1,0,1]
	v_sub_f32_e32 v62, v58, v78
	v_mul_f32_e32 v60, v65, v69
	v_pk_fma_f32 v[86:87], v[64:65], v[68:69], v[60:61] op_sel_hi:[1,1,0] neg_lo:[0,0,1] neg_hi:[0,0,1]
	v_mul_f32_e32 v60, v64, v69
	v_pk_fma_f32 v[88:89], v[64:65], v[68:69], v[60:61] op_sel:[1,0,0] op_sel_hi:[0,1,0]
	v_sub_f32_e32 v60, v76, v84
	v_mov_b32_e32 v76, v80
	v_mov_b32_e32 v77, v82
	v_mov_b32_e32 v64, v86
	v_mov_b32_e32 v65, v88

.LBB0_398:
.LBB0_399:
	v_pk_mul_f32 v[60:61], v[152:153], v[48:49] op_sel_hi:[0,1]
	v_pk_mul_f32 v[46:47], v[152:153], v[46:47] op_sel_hi:[0,1]
	v_pk_mul_f32 v[48:49], v[152:153], v[44:45] op_sel_hi:[0,1]
	s_and_b64 vcc, exec, s[36:37]
	v_pk_mul_f32 v[44:45], v[152:153], v[42:43] op_sel_hi:[0,1]
	s_cbranch_vccnz .LBB0_401
	s_waitcnt vmcnt(0)
	v_pk_mul_f32 v[62:63], v[46:47], v[54:55] op_sel:[1,1] op_sel_hi:[0,1]
	v_pk_mul_f32 v[42:43], v[46:47], v[54:55]
	v_pk_fma_f32 v[46:47], v[46:47], v[54:55], v[62:63] op_sel_hi:[1,0,1]
	v_pk_mul_f32 v[68:69], v[44:45], v[50:51] op_sel:[1,1] op_sel_hi:[0,1]
	v_mul_f32_e32 v46, v61, v57
	v_pk_fma_f32 v[64:65], v[60:61], v[56:57], v[46:47] op_sel_hi:[1,1,0] neg_lo:[0,0,1] neg_hi:[0,0,1]
	v_mul_f32_e32 v46, v60, v57
	v_pk_fma_f32 v[66:67], v[60:61], v[56:57], v[46:47] op_sel:[1,0,0] op_sel_hi:[0,1,0]
	v_pk_mul_f32 v[60:61], v[44:45], v[50:51]
	v_pk_fma_f32 v[44:45], v[44:45], v[50:51], v[68:69] op_sel_hi:[1,0,1]
	v_sub_f32_e32 v46, v42, v62
	v_mul_f32_e32 v44, v49, v53
	v_pk_fma_f32 v[70:71], v[48:49], v[52:53], v[44:45] op_sel_hi:[1,1,0] neg_lo:[0,0,1] neg_hi:[0,0,1]
	v_mul_f32_e32 v44, v48, v53
	v_pk_fma_f32 v[72:73], v[48:49], v[52:53], v[44:45] op_sel:[1,0,0] op_sel_hi:[0,1,0]
	v_sub_f32_e32 v44, v60, v68
	v_mov_b32_e32 v60, v64
	v_mov_b32_e32 v61, v66
	v_mov_b32_e32 v48, v70
	v_mov_b32_e32 v49, v72

.LBB0_405:
.LBB0_406:
	v_pk_mul_f32 v[44:45], v[144:145], v[32:33] op_sel_hi:[0,1]
	v_pk_mul_f32 v[30:31], v[144:145], v[30:31] op_sel_hi:[0,1]
	v_pk_mul_f32 v[32:33], v[144:145], v[28:29] op_sel_hi:[0,1]
	s_and_b64 vcc, exec, s[36:37]
	v_pk_mul_f32 v[28:29], v[144:145], v[26:27] op_sel_hi:[0,1]
	s_cbranch_vccnz .LBB0_408
	s_waitcnt vmcnt(0)
	v_pk_mul_f32 v[46:47], v[30:31], v[38:39] op_sel:[1,1] op_sel_hi:[0,1]
	v_pk_mul_f32 v[26:27], v[30:31], v[38:39]
	v_pk_fma_f32 v[30:31], v[30:31], v[38:39], v[46:47] op_sel_hi:[1,0,1]
	v_pk_mul_f32 v[52:53], v[28:29], v[34:35] op_sel:[1,1] op_sel_hi:[0,1]
	v_mul_f32_e32 v30, v45, v41
	v_pk_fma_f32 v[48:49], v[44:45], v[40:41], v[30:31] op_sel_hi:[1,1,0] neg_lo:[0,0,1] neg_hi:[0,0,1]
	v_mul_f32_e32 v30, v44, v41
	v_pk_fma_f32 v[50:51], v[44:45], v[40:41], v[30:31] op_sel:[1,0,0] op_sel_hi:[0,1,0]
	v_pk_mul_f32 v[44:45], v[28:29], v[34:35]
	v_pk_fma_f32 v[28:29], v[28:29], v[34:35], v[52:53] op_sel_hi:[1,0,1]
	v_sub_f32_e32 v30, v26, v46
	v_mul_f32_e32 v28, v33, v37
	v_pk_fma_f32 v[54:55], v[32:33], v[36:37], v[28:29] op_sel_hi:[1,1,0] neg_lo:[0,0,1] neg_hi:[0,0,1]
	v_mul_f32_e32 v28, v32, v37
	v_pk_fma_f32 v[56:57], v[32:33], v[36:37], v[28:29] op_sel:[1,0,0] op_sel_hi:[0,1,0]
	v_sub_f32_e32 v28, v44, v52
	v_mov_b32_e32 v44, v48
	v_mov_b32_e32 v45, v50
	v_mov_b32_e32 v32, v54
	v_mov_b32_e32 v33, v56

.LBB0_412:
.LBB0_413:
	v_mov_b32_e32 v30, v145
	v_pk_mul_f32 v[28:29], v[30:31], v[16:17] op_sel_hi:[0,1]
	v_pk_mul_f32 v[14:15], v[30:31], v[14:15] op_sel_hi:[0,1]
	v_pk_mul_f32 v[16:17], v[30:31], v[12:13] op_sel_hi:[0,1]
	s_and_b64 vcc, exec, s[36:37]
	v_pk_mul_f32 v[12:13], v[30:31], v[10:11] op_sel_hi:[0,1]
	s_cbranch_vccnz .LBB0_415
	s_waitcnt vmcnt(0)
	v_pk_mul_f32 v[30:31], v[14:15], v[22:23] op_sel:[1,1] op_sel_hi:[0,1]
	v_pk_mul_f32 v[10:11], v[14:15], v[22:23]
	v_pk_fma_f32 v[14:15], v[14:15], v[22:23], v[30:31] op_sel_hi:[1,0,1]
	v_pk_mul_f32 v[36:37], v[12:13], v[18:19] op_sel:[1,1] op_sel_hi:[0,1]
	v_mul_f32_e32 v14, v29, v25
	v_pk_fma_f32 v[32:33], v[28:29], v[24:25], v[14:15] op_sel_hi:[1,1,0] neg_lo:[0,0,1] neg_hi:[0,0,1]
	v_mul_f32_e32 v14, v28, v25
	v_pk_fma_f32 v[34:35], v[28:29], v[24:25], v[14:15] op_sel:[1,0,0] op_sel_hi:[0,1,0]
	v_pk_mul_f32 v[28:29], v[12:13], v[18:19]
	v_pk_fma_f32 v[12:13], v[12:13], v[18:19], v[36:37] op_sel_hi:[1,0,1]
	v_sub_f32_e32 v14, v10, v30
	v_mul_f32_e32 v12, v17, v21
	v_pk_fma_f32 v[38:39], v[16:17], v[20:21], v[12:13] op_sel_hi:[1,1,0] neg_lo:[0,0,1] neg_hi:[0,0,1]
	v_mul_f32_e32 v12, v16, v21
	v_pk_fma_f32 v[40:41], v[16:17], v[20:21], v[12:13] op_sel:[1,0,0] op_sel_hi:[0,1,0]
	v_sub_f32_e32 v12, v28, v36
	v_mov_b32_e32 v28, v32
	v_mov_b32_e32 v29, v34
	v_mov_b32_e32 v16, v38
	v_mov_b32_e32 v17, v40

.LBB0_1118:
	v_lshl_add_u32 v150, s40, 8, v1
	s_cmp_lt_i32 s38, 0
	s_cselect_b64 s[40:41], -1, 0
	s_cmp_gt_i32 s38, -1
	v_ashrrev_i32_e32 v151, 31, v150
	s_cbranch_scc0 .LBB0_1161
	v_cndmask_b32_e64 v152, 0, 1, s[40:41]
	v_cmp_ne_u32_e64 s[36:37], 1, v152
	s_andn2_b64 vcc, exec, s[40:41]
	s_cbranch_vccnz .LBB0_1121

.LBB0_1123:
	v_or_b32_e32 v122, 16, v150
	s_and_b64 vcc, exec, s[36:37]
	v_ashrrev_i32_e32 v123, 31, v122
	v_cvt_pk_bf16_f32 v118, v118, v119
	v_cvt_pk_bf16_f32 v119, v120, v121
	v_cvt_pk_bf16_f32 v120, v114, v115
	v_cvt_pk_bf16_f32 v121, v116, v117
	global_store_dwordx4 v[154:155], v[118:121], off offset:256
	s_cbranch_vccz .LBB0_1162
	s_nop 0
	s_and_b64 vcc, exec, s[36:37]
	s_cbranch_vccnz .LBB0_1126

.LBB0_1128:
	v_or_b32_e32 v106, 32, v150
	s_and_b64 vcc, exec, s[36:37]
	v_ashrrev_i32_e32 v107, 31, v106
	v_cvt_pk_bf16_f32 v102, v102, v103
	v_cvt_pk_bf16_f32 v103, v104, v105
	v_cvt_pk_bf16_f32 v104, v98, v99
	v_cvt_pk_bf16_f32 v105, v100, v101
	global_store_dwordx4 v[122:123], v[102:105], off offset:256
	s_cbranch_vccz .LBB0_1163
	s_nop 0
	s_and_b64 vcc, exec, s[36:37]
	s_cbranch_vccnz .LBB0_1131

.LBB0_1133:
	v_or_b32_e32 v90, 48, v150
	s_and_b64 vcc, exec, s[36:37]
	v_ashrrev_i32_e32 v91, 31, v90
	v_cvt_pk_bf16_f32 v86, v86, v87
	v_cvt_pk_bf16_f32 v87, v88, v89
	v_cvt_pk_bf16_f32 v88, v82, v83
	v_cvt_pk_bf16_f32 v89, v84, v85
	global_store_dwordx4 v[106:107], v[86:89], off offset:256
	s_cbranch_vccz .LBB0_1164
	s_nop 0
	s_and_b64 vcc, exec, s[36:37]
	s_cbranch_vccnz .LBB0_1136

.LBB0_1138:
	v_add_u32_e32 v74, 0x80, v150
	s_and_b64 vcc, exec, s[36:37]
	v_ashrrev_i32_e32 v75, 31, v74
	v_cvt_pk_bf16_f32 v70, v70, v71
	v_cvt_pk_bf16_f32 v71, v72, v73
	v_cvt_pk_bf16_f32 v72, v66, v67
	v_cvt_pk_bf16_f32 v73, v68, v69
	global_store_dwordx4 v[90:91], v[70:73], off offset:256
	s_cbranch_vccz .LBB0_1165
	s_nop 0
	s_and_b64 vcc, exec, s[36:37]
	s_cbranch_vccnz .LBB0_1141

.LBB0_1143:
	v_add_u32_e32 v58, 0x90, v150
	s_and_b64 vcc, exec, s[36:37]
	v_ashrrev_i32_e32 v59, 31, v58
	v_cvt_pk_bf16_f32 v54, v54, v55
	v_cvt_pk_bf16_f32 v55, v56, v57
	v_cvt_pk_bf16_f32 v56, v50, v51
	v_cvt_pk_bf16_f32 v57, v52, v53
	global_store_dwordx4 v[74:75], v[54:57], off offset:256
	s_cbranch_vccz .LBB0_1166
	s_nop 0
	s_and_b64 vcc, exec, s[36:37]
	s_cbranch_vccnz .LBB0_1146

.LBB0_1148:
	v_add_u32_e32 v42, 0xa0, v150
	s_and_b64 vcc, exec, s[36:37]
	v_ashrrev_i32_e32 v43, 31, v42
	v_cvt_pk_bf16_f32 v38, v38, v39
	v_cvt_pk_bf16_f32 v39, v40, v41
	v_cvt_pk_bf16_f32 v40, v34, v35
	v_cvt_pk_bf16_f32 v41, v36, v37
	global_store_dwordx4 v[58:59], v[38:41], off offset:256
	s_cbranch_vccz .LBB0_1167
	s_nop 0
	s_and_b64 vcc, exec, s[36:37]
	s_cbranch_vccnz .LBB0_1151

.LBB0_1153:
	v_add_u32_e32 v26, 0xb0, v150
	s_and_b64 vcc, exec, s[36:37]
	v_ashrrev_i32_e32 v27, 31, v26
	v_cvt_pk_bf16_f32 v22, v22, v23
	v_cvt_pk_bf16_f32 v23, v24, v25
	v_cvt_pk_bf16_f32 v24, v18, v19
	v_cvt_pk_bf16_f32 v25, v20, v21
	global_store_dwordx4 v[42:43], v[22:25], off offset:256
	s_cbranch_vccz .LBB0_1168
	s_nop 0
	s_and_b64 vcc, exec, s[36:37]
	s_cbranch_vccnz .LBB0_1156

.LBB0_1304:
	v_cvt_pk_bf16_f32 v118, v118, v119
	v_cvt_pk_bf16_f32 v119, v120, v121
	v_cvt_pk_bf16_f32 v120, v114, v115
	v_cvt_pk_bf16_f32 v121, v116, v117
	global_store_dwordx4 v[124:125], v[118:121], off offset:256
	v_or_b32_e32 v124, 16, v164
	s_and_b64 vcc, exec, s[36:37]
	v_ashrrev_i32_e32 v125, 31, v124
	s_cbranch_vccz .LBB0_1306
	s_branch .LBB0_1307

.LBB0_1311:
	v_cvt_pk_bf16_f32 v102, v102, v103
	v_cvt_pk_bf16_f32 v103, v104, v105
	v_cvt_pk_bf16_f32 v104, v98, v99
	v_cvt_pk_bf16_f32 v105, v100, v101
	global_store_dwordx4 v[106:107], v[102:105], off offset:256
	v_or_b32_e32 v106, 32, v164
	s_and_b64 vcc, exec, s[36:37]
	v_ashrrev_i32_e32 v107, 31, v106
	s_cbranch_vccz .LBB0_1313
	s_branch .LBB0_1314

.LBB0_1318:
	v_cvt_pk_bf16_f32 v86, v86, v87
	v_cvt_pk_bf16_f32 v87, v88, v89
	v_cvt_pk_bf16_f32 v88, v82, v83
	v_cvt_pk_bf16_f32 v89, v84, v85
	global_store_dwordx4 v[90:91], v[86:89], off offset:256
	v_or_b32_e32 v90, 48, v164
	s_and_b64 vcc, exec, s[36:37]
	v_ashrrev_i32_e32 v91, 31, v90
	s_cbranch_vccz .LBB0_1320
	s_branch .LBB0_1321

.LBB0_1325:
	v_cvt_pk_bf16_f32 v70, v70, v71
	v_cvt_pk_bf16_f32 v71, v72, v73
	v_cvt_pk_bf16_f32 v72, v66, v67
	v_cvt_pk_bf16_f32 v73, v68, v69
	global_store_dwordx4 v[74:75], v[70:73], off offset:256
	v_add_u32_e32 v74, 0x80, v164
	s_and_b64 vcc, exec, s[36:37]
	v_ashrrev_i32_e32 v75, 31, v74
	s_cbranch_vccz .LBB0_1327
	s_branch .LBB0_1328

.LBB0_1332:
	v_cvt_pk_bf16_f32 v54, v54, v55
	v_cvt_pk_bf16_f32 v55, v56, v57
	v_cvt_pk_bf16_f32 v56, v50, v51
	v_cvt_pk_bf16_f32 v57, v52, v53
	global_store_dwordx4 v[58:59], v[54:57], off offset:256
	v_add_u32_e32 v58, 0x90, v164
	s_and_b64 vcc, exec, s[36:37]
	v_ashrrev_i32_e32 v59, 31, v58
	s_cbranch_vccz .LBB0_1334
	s_branch .LBB0_1335

.LBB0_1339:
	v_cvt_pk_bf16_f32 v38, v38, v39
	v_cvt_pk_bf16_f32 v39, v40, v41
	v_cvt_pk_bf16_f32 v40, v34, v35
	v_cvt_pk_bf16_f32 v41, v36, v37
	global_store_dwordx4 v[42:43], v[38:41], off offset:256
	v_add_u32_e32 v42, 0xa0, v164
	s_and_b64 vcc, exec, s[36:37]
	v_ashrrev_i32_e32 v43, 31, v42
	s_cbranch_vccz .LBB0_1341
	s_branch .LBB0_1342

.LBB0_1346:
	v_cvt_pk_bf16_f32 v22, v22, v23
	v_cvt_pk_bf16_f32 v23, v24, v25
	v_cvt_pk_bf16_f32 v24, v18, v19
	v_cvt_pk_bf16_f32 v25, v20, v21
	global_store_dwordx4 v[26:27], v[22:25], off offset:256
	v_add_u32_e32 v26, 0xb0, v164
	s_and_b64 vcc, exec, s[36:37]
	v_ashrrev_i32_e32 v27, 31, v26
	s_cbranch_vccz .LBB0_1348
	s_branch .LBB0_1349

.LBB0_1624:
	v_lshl_add_u32 v150, s38, 8, v1
	s_cmp_lt_i32 s40, 0
	s_cselect_b64 s[42:43], -1, 0
	s_cmp_gt_i32 s40, -1
	v_ashrrev_i32_e32 v151, 31, v150
	s_cbranch_scc0 .LBB0_1667
	v_cndmask_b32_e64 v152, 0, 1, s[42:43]
	v_cmp_ne_u32_e64 s[38:39], 1, v152
	s_andn2_b64 vcc, exec, s[42:43]
	s_cbranch_vccnz .LBB0_1627

.LBB0_1629:
	v_or_b32_e32 v122, 16, v150
	s_and_b64 vcc, exec, s[38:39]
	v_ashrrev_i32_e32 v123, 31, v122
	v_cvt_pk_bf16_f32 v118, v118, v119
	v_cvt_pk_bf16_f32 v119, v120, v121
	v_cvt_pk_bf16_f32 v120, v114, v115
	v_cvt_pk_bf16_f32 v121, v116, v117
	global_store_dwordx4 v[154:155], v[118:121], off offset:256
	s_cbranch_vccz .LBB0_1668
	s_nop 0
	s_and_b64 vcc, exec, s[38:39]
	s_cbranch_vccnz .LBB0_1632

.LBB0_1634:
	v_or_b32_e32 v106, 32, v150
	s_and_b64 vcc, exec, s[38:39]
	v_ashrrev_i32_e32 v107, 31, v106
	v_cvt_pk_bf16_f32 v102, v102, v103
	v_cvt_pk_bf16_f32 v103, v104, v105
	v_cvt_pk_bf16_f32 v104, v98, v99
	v_cvt_pk_bf16_f32 v105, v100, v101
	global_store_dwordx4 v[122:123], v[102:105], off offset:256
	s_cbranch_vccz .LBB0_1669
	s_nop 0
	s_and_b64 vcc, exec, s[38:39]
	s_cbranch_vccnz .LBB0_1637

.LBB0_1639:
	v_or_b32_e32 v90, 48, v150
	s_and_b64 vcc, exec, s[38:39]
	v_ashrrev_i32_e32 v91, 31, v90
	v_cvt_pk_bf16_f32 v86, v86, v87
	v_cvt_pk_bf16_f32 v87, v88, v89
	v_cvt_pk_bf16_f32 v88, v82, v83
	v_cvt_pk_bf16_f32 v89, v84, v85
	global_store_dwordx4 v[106:107], v[86:89], off offset:256
	s_cbranch_vccz .LBB0_1670
	s_nop 0
	s_and_b64 vcc, exec, s[38:39]
	s_cbranch_vccnz .LBB0_1642

.LBB0_1644:
	v_add_u32_e32 v74, 0x80, v150
	s_and_b64 vcc, exec, s[38:39]
	v_ashrrev_i32_e32 v75, 31, v74
	v_cvt_pk_bf16_f32 v70, v70, v71
	v_cvt_pk_bf16_f32 v71, v72, v73
	v_cvt_pk_bf16_f32 v72, v66, v67
	v_cvt_pk_bf16_f32 v73, v68, v69
	global_store_dwordx4 v[90:91], v[70:73], off offset:256
	s_cbranch_vccz .LBB0_1671
	s_nop 0
	s_and_b64 vcc, exec, s[38:39]
	s_cbranch_vccnz .LBB0_1647

.LBB0_1649:
	v_add_u32_e32 v58, 0x90, v150
	s_and_b64 vcc, exec, s[38:39]
	v_ashrrev_i32_e32 v59, 31, v58
	v_cvt_pk_bf16_f32 v54, v54, v55
	v_cvt_pk_bf16_f32 v55, v56, v57
	v_cvt_pk_bf16_f32 v56, v50, v51
	v_cvt_pk_bf16_f32 v57, v52, v53
	global_store_dwordx4 v[74:75], v[54:57], off offset:256
	s_cbranch_vccz .LBB0_1672
	s_nop 0
	s_and_b64 vcc, exec, s[38:39]
	s_cbranch_vccnz .LBB0_1652

.LBB0_1654:
	v_add_u32_e32 v42, 0xa0, v150
	s_and_b64 vcc, exec, s[38:39]
	v_ashrrev_i32_e32 v43, 31, v42
	v_cvt_pk_bf16_f32 v38, v38, v39
	v_cvt_pk_bf16_f32 v39, v40, v41
	v_cvt_pk_bf16_f32 v40, v34, v35
	v_cvt_pk_bf16_f32 v41, v36, v37
	global_store_dwordx4 v[58:59], v[38:41], off offset:256
	s_cbranch_vccz .LBB0_1673
	s_nop 0
	s_and_b64 vcc, exec, s[38:39]
	s_cbranch_vccnz .LBB0_1657

.LBB0_1659:
	v_add_u32_e32 v26, 0xb0, v150
	s_and_b64 vcc, exec, s[38:39]
	v_ashrrev_i32_e32 v27, 31, v26
	v_cvt_pk_bf16_f32 v22, v22, v23
	v_cvt_pk_bf16_f32 v23, v24, v25
	v_cvt_pk_bf16_f32 v24, v18, v19
	v_cvt_pk_bf16_f32 v25, v20, v21
	global_store_dwordx4 v[42:43], v[22:25], off offset:256
	s_cbranch_vccz .LBB0_1674
	s_nop 0
	s_and_b64 vcc, exec, s[38:39]
	s_cbranch_vccnz .LBB0_1662

.LBB0_1877:
	v_lshl_add_u32 v150, s21, 8, v1
	s_cmp_lt_i32 s8, 0
	s_cselect_b64 s[22:23], -1, 0
	s_cmp_gt_i32 s8, -1
	v_ashrrev_i32_e32 v151, 31, v150
	s_cbranch_scc0 .LBB0_1920
	v_cndmask_b32_e64 v152, 0, 1, s[22:23]
	v_cmp_ne_u32_e64 s[38:39], 1, v152
	s_andn2_b64 vcc, exec, s[22:23]
	s_cbranch_vccnz .LBB0_1880
